# xcd barriers: waiting workgroups poll the top-level generation word directly (per-instance constant) instead of the per-XCD generation word, one hop less in the wake-up chain
# speedup vs baseline: 1.0098x; 1.0098x over previous
; __device__ __forceinline__ unsigned xb_ld(unsigned* p)              { return __hip_atomic_load(p, __ATOMIC_RELAXED, __HIP_MEMORY_SCOPE_AGENT); }
; __device__ __forceinline__ unsigned xb_add(unsigned* p, unsigned v) { return __hip_atomic_fetch_add(p, v, __ATOMIC_RELAXED, __HIP_MEMORY_SCOPE_AGENT); }
; #define XB_SPIN(cond, bar) do { unsigned _sp = 0; while (cond) { __builtin_amdgcn_s_sleep(1); \
;     if ((++_sp & 255u) == 0u) { if (xb_ld(&(bar)[XB_TMO])) break; if (_sp > XB_SPIN_CAP) { atomicAdd(&(bar)[XB_TMO], 1u); break; } } } } while (0)
; __device__ __forceinline__ void xcd_barrier(const XcdBarrier& b) {
;     ...
;     if (threadIdx.x == 0) {
;         unsigned* bar = b.bar;
;         __builtin_amdgcn_s_waitcnt(0);
;         unsigned nloc = b.st[0], nx = b.st[1];
;         if (nloc == 0u) { xcd_barrier_complete(bar, b.x, nloc, nx); b.st[0] = nloc; b.st[1] = nx; }
;         const unsigned old = xb_add(&bar[XB_XSUB(b.x)], 1u);
;         const unsigned gen = old / nloc;
;         if (old + 1u == (gen + 1u) * nloc) {
;             __builtin_amdgcn_fence(__ATOMIC_RELEASE, "agent");
;             asm volatile("s_waitcnt vmcnt(0)" ::: "memory");
;             const unsigned og = xb_add(&bar[XB_TOP], 1u);
;             const unsigned tg = og / nx;
;             if (og + 1u == (tg + 1u) * nx) xb_add(&bar[XB_TOPGEN], 1u);
;             else XB_SPIN(xb_ld(&bar[XB_TOPGEN]) == tg, bar);
;             __builtin_amdgcn_fence(__ATOMIC_ACQUIRE, "agent");
;             xb_add(&bar[XB_XGEN(b.x)], 1u);
;             asm volatile("s_waitcnt vmcnt(0)" ::: "memory");
;         } else {
;             XB_SPIN(xb_ld(&bar[XB_XGEN(b.x)]) == gen, bar);
.LBB0_96:
	v_readlane_b32 s3, v254, 45
	s_lshl_b32 s3, s3, 8
	v_readlane_b32 s6, v254, 43
	v_readlane_b32 s7, v254, 44
	s_add_u32 s6, s6, s3
	s_addc_u32 s7, s7, 0
	v_mov_b32_e32 v1, 0x1000
	v_mov_b32_e32 v3, 1
	v_sub_u32_e32 v4, 0, v2
	global_atomic_add v3, v1, v3, s[6:7] offset:1024 sc0
	v_cvt_f32_u32_e32 v1, v2
	v_rcp_iflag_f32_e32 v1, v1
	s_nop 0
	v_mul_f32_e32 v1, 0x4f7ffffe, v1
	v_cvt_u32_f32_e32 v1, v1
	v_mul_lo_u32 v4, v4, v1
	v_mul_hi_u32 v4, v1, v4
	v_add_u32_e32 v1, v1, v4
	s_waitcnt vmcnt(0)
	v_mul_hi_u32 v1, v3, v1
	v_mul_lo_u32 v4, v1, v2
	v_sub_u32_e32 v4, v3, v4
	v_add_u32_e32 v5, 1, v1
	v_cmp_ge_u32_e32 vcc, v4, v2
	v_add_u32_e32 v3, 1, v3
	s_nop 0
	v_cndmask_b32_e32 v1, v1, v5, vcc
	v_sub_u32_e32 v5, v4, v2
	v_cndmask_b32_e32 v4, v4, v5, vcc
	v_add_u32_e32 v5, 1, v1
	v_cmp_ge_u32_e32 vcc, v4, v2
	s_nop 1
	v_cndmask_b32_e32 v1, v1, v5, vcc
	v_mul_lo_u32 v4, v2, v1
	v_add_u32_e32 v2, v4, v2
	v_cmp_ne_u32_e32 vcc, v3, v2
	s_and_saveexec_b64 s[8:9], vcc
	s_xor_b64 s[8:9], exec, s[8:9]
	s_cbranch_execz .LBB0_110
	s_waitcnt lgkmcnt(0)
	v_mov_b32_e32 v1, 0
	s_add_u32 s14, s78, 0x193e3500
	s_addc_u32 s15, s79, 0
	v_mov_b32_e32 v0, 0
	global_load_dword v0, v0, s[14:15] sc1
	s_waitcnt vmcnt(0)
	v_cmp_eq_u32_e32 vcc, v0, v1
	s_and_saveexec_b64 s[10:11], vcc
	s_cbranch_execz .LBB0_109
	s_add_u32 s12, s78, 0x193e0200
	s_addc_u32 s13, s79, 0
	s_mov_b32 s3, 1
	s_mov_b64 s[16:17], 0
	v_mov_b32_e32 v0, 0
	s_branch .LBB0_100

; __device__ __forceinline__ unsigned xb_ld(unsigned* p)              { return __hip_atomic_load(p, __ATOMIC_RELAXED, __HIP_MEMORY_SCOPE_AGENT); }
; __device__ __forceinline__ unsigned xb_add(unsigned* p, unsigned v) { return __hip_atomic_fetch_add(p, v, __ATOMIC_RELAXED, __HIP_MEMORY_SCOPE_AGENT); }
; #define XB_SPIN(cond, bar) do { unsigned _sp = 0; while (cond) { __builtin_amdgcn_s_sleep(1); \
;     if ((++_sp & 255u) == 0u) { if (xb_ld(&(bar)[XB_TMO])) break; if (_sp > XB_SPIN_CAP) { atomicAdd(&(bar)[XB_TMO], 1u); break; } } } } while (0)
; __device__ __forceinline__ void xcd_barrier(const XcdBarrier& b) {
;     ...
;     if (threadIdx.x == 0) {
;         unsigned* bar = b.bar;
;         __builtin_amdgcn_s_waitcnt(0);
;         unsigned nloc = b.st[0], nx = b.st[1];
;         if (nloc == 0u) { xcd_barrier_complete(bar, b.x, nloc, nx); b.st[0] = nloc; b.st[1] = nx; }
;         const unsigned old = xb_add(&bar[XB_XSUB(b.x)], 1u);
;         const unsigned gen = old / nloc;
;         if (old + 1u == (gen + 1u) * nloc) {
;             __builtin_amdgcn_fence(__ATOMIC_RELEASE, "agent");
;             asm volatile("s_waitcnt vmcnt(0)" ::: "memory");
;             const unsigned og = xb_add(&bar[XB_TOP], 1u);
;             const unsigned tg = og / nx;
;             if (og + 1u == (tg + 1u) * nx) xb_add(&bar[XB_TOPGEN], 1u);
;             else XB_SPIN(xb_ld(&bar[XB_TOPGEN]) == tg, bar);
;             __builtin_amdgcn_fence(__ATOMIC_ACQUIRE, "agent");
;             xb_add(&bar[XB_XGEN(b.x)], 1u);
;             asm volatile("s_waitcnt vmcnt(0)" ::: "memory");
;         } else {
;             XB_SPIN(xb_ld(&bar[XB_XGEN(b.x)]) == gen, bar);
.LBB0_241:
	v_readlane_b32 s3, v254, 45
	s_lshl_b32 s3, s3, 8
	v_readlane_b32 s6, v254, 43
	v_readlane_b32 s7, v254, 44
	s_add_u32 s6, s6, s3
	s_addc_u32 s7, s7, 0
	v_mov_b32_e32 v1, 0x1000
	v_mov_b32_e32 v3, 1
	v_sub_u32_e32 v4, 0, v2
	global_atomic_add v3, v1, v3, s[6:7] offset:1024 sc0
	v_cvt_f32_u32_e32 v1, v2
	v_rcp_iflag_f32_e32 v1, v1
	s_nop 0
	v_mul_f32_e32 v1, 0x4f7ffffe, v1
	v_cvt_u32_f32_e32 v1, v1
	v_mul_lo_u32 v4, v4, v1
	v_mul_hi_u32 v4, v1, v4
	v_add_u32_e32 v1, v1, v4
	s_waitcnt vmcnt(0)
	v_mul_hi_u32 v1, v3, v1
	v_mul_lo_u32 v4, v1, v2
	v_sub_u32_e32 v4, v3, v4
	v_add_u32_e32 v5, 1, v1
	v_cmp_ge_u32_e32 vcc, v4, v2
	v_add_u32_e32 v3, 1, v3
	s_nop 0
	v_cndmask_b32_e32 v1, v1, v5, vcc
	v_sub_u32_e32 v5, v4, v2
	v_cndmask_b32_e32 v4, v4, v5, vcc
	v_add_u32_e32 v5, 1, v1
	v_cmp_ge_u32_e32 vcc, v4, v2
	s_nop 1
	v_cndmask_b32_e32 v1, v1, v5, vcc
	v_mul_lo_u32 v4, v2, v1
	v_add_u32_e32 v2, v4, v2
	v_cmp_ne_u32_e32 vcc, v3, v2
	s_and_saveexec_b64 s[8:9], vcc
	s_xor_b64 s[8:9], exec, s[8:9]
	s_cbranch_execz .LBB0_255
	s_waitcnt lgkmcnt(0)
	v_mov_b32_e32 v1, 1
	s_add_u32 s14, s78, 0x193e3500
	s_addc_u32 s15, s79, 0
	v_mov_b32_e32 v0, 0
	global_load_dword v0, v0, s[14:15] sc1
	s_waitcnt vmcnt(0)
	v_cmp_eq_u32_e32 vcc, v0, v1
	s_and_saveexec_b64 s[10:11], vcc
	s_cbranch_execz .LBB0_254
	s_add_u32 s12, s78, 0x193e0200
	s_addc_u32 s13, s79, 0
	s_mov_b32 s3, 1
	s_mov_b64 s[16:17], 0
	v_mov_b32_e32 v0, 0
	s_branch .LBB0_245

; __device__ __forceinline__ unsigned xb_ld(unsigned* p)              { return __hip_atomic_load(p, __ATOMIC_RELAXED, __HIP_MEMORY_SCOPE_AGENT); }
; __device__ __forceinline__ unsigned xb_add(unsigned* p, unsigned v) { return __hip_atomic_fetch_add(p, v, __ATOMIC_RELAXED, __HIP_MEMORY_SCOPE_AGENT); }
; #define XB_SPIN(cond, bar) do { unsigned _sp = 0; while (cond) { __builtin_amdgcn_s_sleep(1); \
;     if ((++_sp & 255u) == 0u) { if (xb_ld(&(bar)[XB_TMO])) break; if (_sp > XB_SPIN_CAP) { atomicAdd(&(bar)[XB_TMO], 1u); break; } } } } while (0)
; __device__ __forceinline__ void xcd_barrier(const XcdBarrier& b) {
;     ...
;     if (threadIdx.x == 0) {
;         unsigned* bar = b.bar;
;         __builtin_amdgcn_s_waitcnt(0);
;         unsigned nloc = b.st[0], nx = b.st[1];
;         if (nloc == 0u) { xcd_barrier_complete(bar, b.x, nloc, nx); b.st[0] = nloc; b.st[1] = nx; }
;         const unsigned old = xb_add(&bar[XB_XSUB(b.x)], 1u);
;         const unsigned gen = old / nloc;
;         if (old + 1u == (gen + 1u) * nloc) {
;             __builtin_amdgcn_fence(__ATOMIC_RELEASE, "agent");
;             asm volatile("s_waitcnt vmcnt(0)" ::: "memory");
;             const unsigned og = xb_add(&bar[XB_TOP], 1u);
;             const unsigned tg = og / nx;
;             if (og + 1u == (tg + 1u) * nx) xb_add(&bar[XB_TOPGEN], 1u);
;             else XB_SPIN(xb_ld(&bar[XB_TOPGEN]) == tg, bar);
;             __builtin_amdgcn_fence(__ATOMIC_ACQUIRE, "agent");
;             xb_add(&bar[XB_XGEN(b.x)], 1u);
;             asm volatile("s_waitcnt vmcnt(0)" ::: "memory");
;         } else {
;             XB_SPIN(xb_ld(&bar[XB_XGEN(b.x)]) == gen, bar);
.LBB0_337:
	v_readlane_b32 s3, v254, 45
	s_lshl_b32 s3, s3, 8
	v_readlane_b32 s6, v254, 43
	v_readlane_b32 s7, v254, 44
	s_add_u32 s6, s6, s3
	s_addc_u32 s7, s7, 0
	v_mov_b32_e32 v1, 0x1000
	v_mov_b32_e32 v3, 1
	v_sub_u32_e32 v4, 0, v2
	global_atomic_add v3, v1, v3, s[6:7] offset:1024 sc0
	v_cvt_f32_u32_e32 v1, v2
	v_rcp_iflag_f32_e32 v1, v1
	s_nop 0
	v_mul_f32_e32 v1, 0x4f7ffffe, v1
	v_cvt_u32_f32_e32 v1, v1
	v_mul_lo_u32 v4, v4, v1
	v_mul_hi_u32 v4, v1, v4
	v_add_u32_e32 v1, v1, v4
	s_waitcnt vmcnt(0)
	v_mul_hi_u32 v1, v3, v1
	v_mul_lo_u32 v4, v1, v2
	v_sub_u32_e32 v4, v3, v4
	v_add_u32_e32 v5, 1, v1
	v_cmp_ge_u32_e32 vcc, v4, v2
	v_add_u32_e32 v3, 1, v3
	s_nop 0
	v_cndmask_b32_e32 v1, v1, v5, vcc
	v_sub_u32_e32 v5, v4, v2
	v_cndmask_b32_e32 v4, v4, v5, vcc
	v_add_u32_e32 v5, 1, v1
	v_cmp_ge_u32_e32 vcc, v4, v2
	s_nop 1
	v_cndmask_b32_e32 v1, v1, v5, vcc
	v_mul_lo_u32 v4, v2, v1
	v_add_u32_e32 v2, v4, v2
	v_cmp_ne_u32_e32 vcc, v3, v2
	s_and_saveexec_b64 s[8:9], vcc
	s_xor_b64 s[8:9], exec, s[8:9]
	s_cbranch_execz .LBB0_351
	s_waitcnt lgkmcnt(0)
	v_mov_b32_e32 v1, 2
	s_add_u32 s14, s78, 0x193e3500
	s_addc_u32 s15, s79, 0
	v_mov_b32_e32 v0, 0
	global_load_dword v0, v0, s[14:15] sc1
	s_waitcnt vmcnt(0)
	v_cmp_eq_u32_e32 vcc, v0, v1
	s_and_saveexec_b64 s[10:11], vcc
	s_cbranch_execz .LBB0_350
	s_add_u32 s12, s78, 0x193e0200
	s_addc_u32 s13, s79, 0
	s_mov_b32 s3, 1
	s_mov_b64 s[16:17], 0
	v_mov_b32_e32 v0, 0
	s_branch .LBB0_341

; __device__ __forceinline__ unsigned xb_ld(unsigned* p)              { return __hip_atomic_load(p, __ATOMIC_RELAXED, __HIP_MEMORY_SCOPE_AGENT); }
; __device__ __forceinline__ unsigned xb_add(unsigned* p, unsigned v) { return __hip_atomic_fetch_add(p, v, __ATOMIC_RELAXED, __HIP_MEMORY_SCOPE_AGENT); }
; #define XB_SPIN(cond, bar) do { unsigned _sp = 0; while (cond) { __builtin_amdgcn_s_sleep(1); \
;     if ((++_sp & 255u) == 0u) { if (xb_ld(&(bar)[XB_TMO])) break; if (_sp > XB_SPIN_CAP) { atomicAdd(&(bar)[XB_TMO], 1u); break; } } } } while (0)
; __device__ __forceinline__ void xcd_barrier(const XcdBarrier& b) {
;     ...
;     if (threadIdx.x == 0) {
;         unsigned* bar = b.bar;
;         __builtin_amdgcn_s_waitcnt(0);
;         unsigned nloc = b.st[0], nx = b.st[1];
;         if (nloc == 0u) { xcd_barrier_complete(bar, b.x, nloc, nx); b.st[0] = nloc; b.st[1] = nx; }
;         const unsigned old = xb_add(&bar[XB_XSUB(b.x)], 1u);
;         const unsigned gen = old / nloc;
;         if (old + 1u == (gen + 1u) * nloc) {
;             __builtin_amdgcn_fence(__ATOMIC_RELEASE, "agent");
;             asm volatile("s_waitcnt vmcnt(0)" ::: "memory");
;             const unsigned og = xb_add(&bar[XB_TOP], 1u);
;             const unsigned tg = og / nx;
;             if (og + 1u == (tg + 1u) * nx) xb_add(&bar[XB_TOPGEN], 1u);
;             else XB_SPIN(xb_ld(&bar[XB_TOPGEN]) == tg, bar);
;             __builtin_amdgcn_fence(__ATOMIC_ACQUIRE, "agent");
;             xb_add(&bar[XB_XGEN(b.x)], 1u);
;             asm volatile("s_waitcnt vmcnt(0)" ::: "memory");
;         } else {
;             XB_SPIN(xb_ld(&bar[XB_XGEN(b.x)]) == gen, bar);
.LBB0_443:
	v_readlane_b32 s3, v254, 45
	s_lshl_b32 s3, s3, 8
	v_readlane_b32 s6, v254, 43
	v_readlane_b32 s7, v254, 44
	s_add_u32 s6, s6, s3
	s_addc_u32 s7, s7, 0
	v_mov_b32_e32 v1, 0x1000
	v_mov_b32_e32 v3, 1
	v_sub_u32_e32 v4, 0, v2
	global_atomic_add v3, v1, v3, s[6:7] offset:1024 sc0
	v_cvt_f32_u32_e32 v1, v2
	v_rcp_iflag_f32_e32 v1, v1
	s_nop 0
	v_mul_f32_e32 v1, 0x4f7ffffe, v1
	v_cvt_u32_f32_e32 v1, v1
	v_mul_lo_u32 v4, v4, v1
	v_mul_hi_u32 v4, v1, v4
	v_add_u32_e32 v1, v1, v4
	s_waitcnt vmcnt(0)
	v_mul_hi_u32 v1, v3, v1
	v_mul_lo_u32 v4, v1, v2
	v_sub_u32_e32 v4, v3, v4
	v_add_u32_e32 v5, 1, v1
	v_cmp_ge_u32_e32 vcc, v4, v2
	v_add_u32_e32 v3, 1, v3
	s_nop 0
	v_cndmask_b32_e32 v1, v1, v5, vcc
	v_sub_u32_e32 v5, v4, v2
	v_cndmask_b32_e32 v4, v4, v5, vcc
	v_add_u32_e32 v5, 1, v1
	v_cmp_ge_u32_e32 vcc, v4, v2
	s_nop 1
	v_cndmask_b32_e32 v1, v1, v5, vcc
	v_mul_lo_u32 v4, v2, v1
	v_add_u32_e32 v2, v4, v2
	v_cmp_ne_u32_e32 vcc, v3, v2
	s_and_saveexec_b64 s[8:9], vcc
	s_xor_b64 s[8:9], exec, s[8:9]
	s_cbranch_execz .LBB0_457
	s_waitcnt lgkmcnt(0)
	v_mov_b32_e32 v1, 3
	s_add_u32 s14, s78, 0x193e3500
	s_addc_u32 s15, s79, 0
	v_mov_b32_e32 v0, 0
	global_load_dword v0, v0, s[14:15] sc1
	s_waitcnt vmcnt(0)
	v_cmp_eq_u32_e32 vcc, v0, v1
	s_and_saveexec_b64 s[10:11], vcc
	s_cbranch_execz .LBB0_456
	s_add_u32 s12, s78, 0x193e0200
	s_addc_u32 s13, s79, 0
	s_mov_b32 s3, 1
	s_mov_b64 s[16:17], 0
	v_mov_b32_e32 v0, 0
	s_branch .LBB0_447

; __device__ __forceinline__ unsigned xb_ld(unsigned* p)              { return __hip_atomic_load(p, __ATOMIC_RELAXED, __HIP_MEMORY_SCOPE_AGENT); }
; __device__ __forceinline__ unsigned xb_add(unsigned* p, unsigned v) { return __hip_atomic_fetch_add(p, v, __ATOMIC_RELAXED, __HIP_MEMORY_SCOPE_AGENT); }
; #define XB_SPIN(cond, bar) do { unsigned _sp = 0; while (cond) { __builtin_amdgcn_s_sleep(1); \
;     if ((++_sp & 255u) == 0u) { if (xb_ld(&(bar)[XB_TMO])) break; if (_sp > XB_SPIN_CAP) { atomicAdd(&(bar)[XB_TMO], 1u); break; } } } } while (0)
; __device__ __forceinline__ void xcd_barrier(const XcdBarrier& b) {
;     ...
;     if (threadIdx.x == 0) {
;         unsigned* bar = b.bar;
;         __builtin_amdgcn_s_waitcnt(0);
;         unsigned nloc = b.st[0], nx = b.st[1];
;         if (nloc == 0u) { xcd_barrier_complete(bar, b.x, nloc, nx); b.st[0] = nloc; b.st[1] = nx; }
;         const unsigned old = xb_add(&bar[XB_XSUB(b.x)], 1u);
;         const unsigned gen = old / nloc;
;         if (old + 1u == (gen + 1u) * nloc) {
;             __builtin_amdgcn_fence(__ATOMIC_RELEASE, "agent");
;             asm volatile("s_waitcnt vmcnt(0)" ::: "memory");
;             const unsigned og = xb_add(&bar[XB_TOP], 1u);
;             const unsigned tg = og / nx;
;             if (og + 1u == (tg + 1u) * nx) xb_add(&bar[XB_TOPGEN], 1u);
;             else XB_SPIN(xb_ld(&bar[XB_TOPGEN]) == tg, bar);
;             __builtin_amdgcn_fence(__ATOMIC_ACQUIRE, "agent");
;             xb_add(&bar[XB_XGEN(b.x)], 1u);
;             asm volatile("s_waitcnt vmcnt(0)" ::: "memory");
;         } else {
;             XB_SPIN(xb_ld(&bar[XB_XGEN(b.x)]) == gen, bar);
.LBB0_517:
	v_readlane_b32 s3, v254, 45
	s_lshl_b32 s3, s3, 8
	v_readlane_b32 s6, v254, 43
	v_readlane_b32 s7, v254, 44
	s_add_u32 s6, s6, s3
	s_addc_u32 s7, s7, 0
	v_mov_b32_e32 v1, 0x1000
	v_mov_b32_e32 v3, 1
	v_sub_u32_e32 v4, 0, v2
	global_atomic_add v3, v1, v3, s[6:7] offset:1024 sc0
	v_cvt_f32_u32_e32 v1, v2
	v_rcp_iflag_f32_e32 v1, v1
	s_nop 0
	v_mul_f32_e32 v1, 0x4f7ffffe, v1
	v_cvt_u32_f32_e32 v1, v1
	v_mul_lo_u32 v4, v4, v1
	v_mul_hi_u32 v4, v1, v4
	v_add_u32_e32 v1, v1, v4
	s_waitcnt vmcnt(0)
	v_mul_hi_u32 v1, v3, v1
	v_mul_lo_u32 v4, v1, v2
	v_sub_u32_e32 v4, v3, v4
	v_add_u32_e32 v5, 1, v1
	v_cmp_ge_u32_e32 vcc, v4, v2
	v_add_u32_e32 v3, 1, v3
	s_nop 0
	v_cndmask_b32_e32 v1, v1, v5, vcc
	v_sub_u32_e32 v5, v4, v2
	v_cndmask_b32_e32 v4, v4, v5, vcc
	v_add_u32_e32 v5, 1, v1
	v_cmp_ge_u32_e32 vcc, v4, v2
	s_nop 1
	v_cndmask_b32_e32 v1, v1, v5, vcc
	v_mul_lo_u32 v4, v2, v1
	v_add_u32_e32 v2, v4, v2
	v_cmp_ne_u32_e32 vcc, v3, v2
	s_and_saveexec_b64 s[8:9], vcc
	s_xor_b64 s[8:9], exec, s[8:9]
	s_cbranch_execz .LBB0_531
	s_waitcnt lgkmcnt(0)
	v_mov_b32_e32 v1, 4
	s_add_u32 s14, s78, 0x193e3500
	s_addc_u32 s15, s79, 0
	v_mov_b32_e32 v0, 0
	global_load_dword v0, v0, s[14:15] sc1
	s_waitcnt vmcnt(0)
	v_cmp_eq_u32_e32 vcc, v0, v1
	s_and_saveexec_b64 s[10:11], vcc
	s_cbranch_execz .LBB0_530
	s_add_u32 s12, s78, 0x193e0200
	s_addc_u32 s13, s79, 0
	s_mov_b32 s3, 1
	s_mov_b64 s[16:17], 0
	v_mov_b32_e32 v0, 0
	s_branch .LBB0_521

; __device__ __forceinline__ unsigned xb_ld(unsigned* p)              { return __hip_atomic_load(p, __ATOMIC_RELAXED, __HIP_MEMORY_SCOPE_AGENT); }
; __device__ __forceinline__ unsigned xb_add(unsigned* p, unsigned v) { return __hip_atomic_fetch_add(p, v, __ATOMIC_RELAXED, __HIP_MEMORY_SCOPE_AGENT); }
; #define XB_SPIN(cond, bar) do { unsigned _sp = 0; while (cond) { __builtin_amdgcn_s_sleep(1); \
;     if ((++_sp & 255u) == 0u) { if (xb_ld(&(bar)[XB_TMO])) break; if (_sp > XB_SPIN_CAP) { atomicAdd(&(bar)[XB_TMO], 1u); break; } } } } while (0)
; __device__ __forceinline__ void xcd_barrier(const XcdBarrier& b) {
;     ...
;     if (threadIdx.x == 0) {
;         unsigned* bar = b.bar;
;         __builtin_amdgcn_s_waitcnt(0);
;         unsigned nloc = b.st[0], nx = b.st[1];
;         if (nloc == 0u) { xcd_barrier_complete(bar, b.x, nloc, nx); b.st[0] = nloc; b.st[1] = nx; }
;         const unsigned old = xb_add(&bar[XB_XSUB(b.x)], 1u);
;         const unsigned gen = old / nloc;
;         if (old + 1u == (gen + 1u) * nloc) {
;             __builtin_amdgcn_fence(__ATOMIC_RELEASE, "agent");
;             asm volatile("s_waitcnt vmcnt(0)" ::: "memory");
;             const unsigned og = xb_add(&bar[XB_TOP], 1u);
;             const unsigned tg = og / nx;
;             if (og + 1u == (tg + 1u) * nx) xb_add(&bar[XB_TOPGEN], 1u);
;             else XB_SPIN(xb_ld(&bar[XB_TOPGEN]) == tg, bar);
;             __builtin_amdgcn_fence(__ATOMIC_ACQUIRE, "agent");
;             xb_add(&bar[XB_XGEN(b.x)], 1u);
;             asm volatile("s_waitcnt vmcnt(0)" ::: "memory");
;         } else {
;             XB_SPIN(xb_ld(&bar[XB_XGEN(b.x)]) == gen, bar);
.LBB0_577:
	v_readlane_b32 s3, v254, 45
	s_lshl_b32 s3, s3, 8
	v_readlane_b32 s6, v254, 43
	v_readlane_b32 s7, v254, 44
	s_add_u32 s6, s6, s3
	s_addc_u32 s7, s7, 0
	v_mov_b32_e32 v1, 0x1000
	v_mov_b32_e32 v3, 1
	v_sub_u32_e32 v4, 0, v2
	global_atomic_add v3, v1, v3, s[6:7] offset:1024 sc0
	v_cvt_f32_u32_e32 v1, v2
	v_rcp_iflag_f32_e32 v1, v1
	s_nop 0
	v_mul_f32_e32 v1, 0x4f7ffffe, v1
	v_cvt_u32_f32_e32 v1, v1
	v_mul_lo_u32 v4, v4, v1
	v_mul_hi_u32 v4, v1, v4
	v_add_u32_e32 v1, v1, v4
	s_waitcnt vmcnt(0)
	v_mul_hi_u32 v1, v3, v1
	v_mul_lo_u32 v4, v1, v2
	v_sub_u32_e32 v4, v3, v4
	v_add_u32_e32 v5, 1, v1
	v_cmp_ge_u32_e32 vcc, v4, v2
	v_add_u32_e32 v3, 1, v3
	s_nop 0
	v_cndmask_b32_e32 v1, v1, v5, vcc
	v_sub_u32_e32 v5, v4, v2
	v_cndmask_b32_e32 v4, v4, v5, vcc
	v_add_u32_e32 v5, 1, v1
	v_cmp_ge_u32_e32 vcc, v4, v2
	s_nop 1
	v_cndmask_b32_e32 v1, v1, v5, vcc
	v_mul_lo_u32 v4, v2, v1
	v_add_u32_e32 v2, v4, v2
	v_cmp_ne_u32_e32 vcc, v3, v2
	s_and_saveexec_b64 s[8:9], vcc
	s_xor_b64 s[8:9], exec, s[8:9]
	s_cbranch_execz .LBB0_591
	s_waitcnt lgkmcnt(0)
	v_mov_b32_e32 v1, 5
	s_add_u32 s14, s78, 0x193e3500
	s_addc_u32 s15, s79, 0
	v_mov_b32_e32 v0, 0
	global_load_dword v0, v0, s[14:15] sc1
	s_waitcnt vmcnt(0)
	v_cmp_eq_u32_e32 vcc, v0, v1
	s_and_saveexec_b64 s[10:11], vcc
	s_cbranch_execz .LBB0_590
	s_add_u32 s12, s78, 0x193e0200
	s_addc_u32 s13, s79, 0
	s_mov_b32 s3, 1
	s_mov_b64 s[16:17], 0
	v_mov_b32_e32 v0, 0
	s_branch .LBB0_581
